# ph6/13 tile remap variant: mt from low bits (CU mates share A rows)
# speedup vs baseline: 1.0051x; 1.0020x over previous
.LBB0_563:
	s_and_b32 s101, s50, 0xffffff00
	s_and_b32 s100, s50, 0xc0
	s_lshr_b32 s100, s100, 3
	s_or_b32 s101, s101, s100
	s_and_b32 s100, s50, 56
	s_lshr_b32 s100, s100, 3
	s_or_b32 s101, s101, s100
	s_and_b32 s100, s50, 7
	s_lshl_b32 s100, s100, 5
	s_or_b32 s101, s101, s100
	s_ashr_i32 s44, s101, 31
	v_mov_b32_e32 v10, v1
	s_lshr_b32 s44, s44, 27
	s_add_i32 s44, s101, s44
	v_lshrrev_b32_e32 v2, 2, v10
	v_and_b32_e32 v2, 12, v2
	s_ashr_i32 s46, s44, 5
	v_lshrrev_b32_e64 v2, v2, s41
	s_andn2_b32 s44, s44, 31
	s_ashr_i32 s47, s46, 31
	v_xor_b32_e32 v2, v2, v10
	v_lshlrev_b32_e32 v3, 8, v10
	s_sub_i32 s44, s101, s44
	s_lshl_b64 s[48:49], s[46:47], 19
	v_and_b32_e32 v3, 0xfffffc00, v3
	v_lshlrev_b32_e32 v2, 3, v2
	s_add_u32 s52, s3, s48
	v_and_or_b32 v2, v2, 24, v3
	v_and_b32_e32 v3, 12, v10
	s_addc_u32 s53, s33, s49
	s_ashr_i32 s45, s44, 31
	v_lshl_add_u32 v138, v10, 4, 0
	v_lshrrev_b32_e64 v11, v3, s42
	v_ashrrev_i32_e32 v3, 31, v2
	s_lshl_b64 s[54:55], s[44:45], 18
	v_lshlrev_b64 v[2:3], 1, v[2:3]
	v_readfirstlane_b32 s45, v138
	v_add_u32_e32 v9, 0x1000, v138
	v_lshl_add_u64 v[4:5], s[52:53], 0, v[2:3]
	s_mov_b32 m0, s45
	v_readfirstlane_b32 s45, v9
	v_add_u32_e32 v9, 0x2000, v138
	v_lshlrev_b32_e32 v8, 6, v10
	global_load_lds_dwordx4 v[4:5], off
	v_lshl_add_u64 v[6:7], v[4:5], 0, s[10:11]
	s_mov_b32 m0, s45
	v_readfirstlane_b32 s45, v9
	v_add_u32_e32 v9, 0x3000, v138
	s_add_u32 s56, s36, s54
	v_and_b32_e32 v139, 0x13c0, v8
	global_load_lds_dwordx4 v[6:7], off
	v_lshl_add_u64 v[6:7], v[4:5], 0, s[12:13]
	s_mov_b32 m0, s45
	v_readfirstlane_b32 s45, v9
	v_and_b32_e32 v140, 0xffffe3c0, v8
	v_add_u32_e32 v8, 0x4000, v138
	s_addc_u32 s57, s37, s55
	global_load_lds_dwordx4 v[6:7], off
	v_lshl_add_u64 v[6:7], v[4:5], 0, s[14:15]
	s_mov_b32 m0, s45
	v_readfirstlane_b32 s45, v8
	v_add_u32_e32 v12, 0x5000, v138
	global_load_lds_dwordx4 v[6:7], off
	v_lshl_add_u64 v[6:7], s[56:57], 0, v[2:3]
	s_mov_b32 m0, s45
	v_readfirstlane_b32 s45, v12
	v_bitop3_b32 v141, v11, 48, v10 bitop3:0x48
	v_add_u32_e32 v10, 0x6000, v138
	global_load_lds_dwordx4 v[6:7], off
	v_lshl_add_u64 v[8:9], v[6:7], 0, s[10:11]
	s_mov_b32 m0, s45
	v_readfirstlane_b32 s45, v10
	v_add_u32_e32 v10, 0x7000, v138
	global_load_lds_dwordx4 v[8:9], off
	v_lshl_add_u64 v[8:9], v[4:5], 0, 64
	s_mov_b32 m0, s45
	v_readfirstlane_b32 s45, v10
	v_add_u32_e32 v10, 0x8000, v138
	global_load_lds_dwordx4 v[8:9], off
	v_lshl_add_u64 v[8:9], v[4:5], 0, s[16:17]
	s_mov_b32 m0, s45
	v_readfirstlane_b32 s45, v10
	global_load_lds_dwordx4 v[8:9], off
	v_lshl_add_u64 v[8:9], v[4:5], 0, s[18:19]
	s_mov_b32 m0, s45
	v_lshl_add_u64 v[4:5], v[4:5], 0, s[20:21]
	global_load_lds_dwordx4 v[8:9], off
	v_add_u32_e32 v8, 0x9000, v138
	s_add_u32 s52, s4, s54
	v_readfirstlane_b32 s45, v8
	v_add_u32_e32 v8, 0xa000, v138
	s_mov_b32 m0, s45
	v_readfirstlane_b32 s45, v8
	global_load_lds_dwordx4 v[4:5], off
	v_lshl_add_u64 v[4:5], v[6:7], 0, 64
	s_mov_b32 m0, s45
	s_addc_u32 s53, s5, s55
	global_load_lds_dwordx4 v[4:5], off
	v_lshl_add_u64 v[4:5], v[6:7], 0, s[16:17]
	v_add_u32_e32 v6, 0xb000, v138
	s_add_u32 s48, s4, s48
	v_readfirstlane_b32 s45, v6
	s_mov_b32 m0, s45
	s_addc_u32 s49, s5, s49
	global_load_lds_dwordx4 v[4:5], off
	v_lshl_add_u64 v[132:133], s[52:53], 0, v[2:3]
	v_lshl_add_u64 v[134:135], s[48:49], 0, v[2:3]
	v_mov_b32_e32 v2, 0
	s_mov_b64 s[48:49], 0
	s_mov_b32 s45, 0
	v_mov_b32_e32 v3, v2
	v_mov_b32_e32 v4, v2
	v_mov_b32_e32 v5, v2
	v_mov_b32_e32 v6, v2
	v_mov_b32_e32 v7, v2
	v_mov_b32_e32 v8, v2
	v_mov_b32_e32 v9, v2
	v_mov_b32_e32 v10, v2
	v_mov_b32_e32 v11, v2
	v_mov_b32_e32 v12, v2
	v_mov_b32_e32 v13, v2
	v_mov_b32_e32 v14, v2
	v_mov_b32_e32 v15, v2
	v_mov_b32_e32 v16, v2
	v_mov_b32_e32 v17, v2
	v_mov_b32_e32 v18, v2
	v_mov_b32_e32 v19, v2
	v_mov_b32_e32 v20, v2
	v_mov_b32_e32 v21, v2
	v_mov_b32_e32 v22, v2
	v_mov_b32_e32 v23, v2
	v_mov_b32_e32 v24, v2
	v_mov_b32_e32 v25, v2
	v_mov_b32_e32 v26, v2
	v_mov_b32_e32 v27, v2
	v_mov_b32_e32 v28, v2
	v_mov_b32_e32 v29, v2
	v_mov_b32_e32 v30, v2
	v_mov_b32_e32 v31, v2
	v_mov_b32_e32 v32, v2
	v_mov_b32_e32 v33, v2
	v_mov_b32_e32 v34, v2
	v_mov_b32_e32 v35, v2
	v_mov_b32_e32 v36, v2
	v_mov_b32_e32 v37, v2
	v_mov_b32_e32 v38, v2
	v_mov_b32_e32 v39, v2
	v_mov_b32_e32 v40, v2
	v_mov_b32_e32 v41, v2
	v_mov_b32_e32 v42, v2
	v_mov_b32_e32 v43, v2
	v_mov_b32_e32 v44, v2
	v_mov_b32_e32 v45, v2
	v_mov_b32_e32 v46, v2
	v_mov_b32_e32 v47, v2
	v_mov_b32_e32 v48, v2
	v_mov_b32_e32 v49, v2
	v_mov_b32_e32 v50, v2
	v_mov_b32_e32 v51, v2
	v_mov_b32_e32 v52, v2
	v_mov_b32_e32 v53, v2
	v_mov_b32_e32 v54, v2
	v_mov_b32_e32 v55, v2
	v_mov_b32_e32 v56, v2
	v_mov_b32_e32 v57, v2
	v_mov_b32_e32 v58, v2
	v_mov_b32_e32 v59, v2
	v_mov_b32_e32 v60, v2
	v_mov_b32_e32 v61, v2
	v_mov_b32_e32 v62, v2
	v_mov_b32_e32 v63, v2
	v_mov_b32_e32 v64, v2
	v_mov_b32_e32 v65, v2
	v_mov_b32_e32 v66, v2
	v_mov_b32_e32 v67, v2
	v_mov_b32_e32 v68, v2
	v_mov_b32_e32 v69, v2
	v_mov_b32_e32 v70, v2
	v_mov_b32_e32 v71, v2
	v_mov_b32_e32 v72, v2
	v_mov_b32_e32 v73, v2
	v_mov_b32_e32 v74, v2
	v_mov_b32_e32 v75, v2
	v_mov_b32_e32 v76, v2
	v_mov_b32_e32 v77, v2
	v_mov_b32_e32 v78, v2
	v_mov_b32_e32 v79, v2
	v_mov_b32_e32 v80, v2
	v_mov_b32_e32 v81, v2
	v_mov_b32_e32 v82, v2
	v_mov_b32_e32 v83, v2
	v_mov_b32_e32 v84, v2
	v_mov_b32_e32 v85, v2
	v_mov_b32_e32 v86, v2
	v_mov_b32_e32 v87, v2
	v_mov_b32_e32 v88, v2
	v_mov_b32_e32 v89, v2
	v_mov_b32_e32 v90, v2
	v_mov_b32_e32 v91, v2
	v_mov_b32_e32 v92, v2
	v_mov_b32_e32 v93, v2
	v_mov_b32_e32 v94, v2
	v_mov_b32_e32 v95, v2
	v_mov_b32_e32 v96, v2
	v_mov_b32_e32 v97, v2
	v_mov_b32_e32 v98, v2
	v_mov_b32_e32 v99, v2
	v_mov_b32_e32 v100, v2
	v_mov_b32_e32 v101, v2
	v_mov_b32_e32 v102, v2
	v_mov_b32_e32 v103, v2
	v_mov_b32_e32 v104, v2
	v_mov_b32_e32 v105, v2
	v_mov_b32_e32 v106, v2
	v_mov_b32_e32 v107, v2
	v_mov_b32_e32 v108, v2
	v_mov_b32_e32 v109, v2
	v_mov_b32_e32 v110, v2
	v_mov_b32_e32 v111, v2
	v_mov_b32_e32 v112, v2
	v_mov_b32_e32 v113, v2
	v_mov_b32_e32 v114, v2
	v_mov_b32_e32 v115, v2
	v_mov_b32_e32 v116, v2
	v_mov_b32_e32 v117, v2
	v_mov_b32_e32 v118, v2
	v_mov_b32_e32 v119, v2
	v_mov_b32_e32 v120, v2
	v_mov_b32_e32 v121, v2
	v_mov_b32_e32 v122, v2
	v_mov_b32_e32 v123, v2
	v_mov_b32_e32 v124, v2
	v_mov_b32_e32 v125, v2
	v_mov_b32_e32 v126, v2
	v_mov_b32_e32 v127, v2
	v_mov_b32_e32 v128, v2
	v_mov_b32_e32 v129, v2
